# LDS-DMA pieces and hosted loads-stores issued between the tile's last back-to-back PV MFMAs
# speedup vs baseline: 1.0047x; 1.0047x over previous
.LBB0_1451:
	s_add_i32 s34, s49, 0xfffe8000
	s_and_b32 s34, s34, 0x18000
	s_add_i32 s34, s34, 0
	v_add3_u32 v84, s34, v177, v176
	ds_read_b128 v[80:83], v84
	ds_read_b128 v[184:187], v84 offset:512
	v_add3_u32 v85, s34, v178, v176
	v_add3_u32 v84, s34, v179, v176
	v_add_u32_e32 v200, s34, v168
	v_add_u32_e32 v201, s34, v169
	s_and_b64 vcc, exec, s[26:27]
	s_waitcnt lgkmcnt(0)
	v_mfma_f32_32x32x16_bf16 v[96:111], v[80:83], v[112:115], v[0:15]
	ds_read_b128 v[80:83], v85 offset:2048
	ds_read_b128 v[188:191], v85 offset:2560
	v_add3_u32 v85, s34, v180, v176
	s_mov_b64 s[34:35], -1
	ds_read_b128 v[192:195], v84 offset:4608
	s_waitcnt lgkmcnt(0)
	v_mfma_f32_32x32x16_bf16 v[96:111], v[80:83], v[116:119], v[96:111]
	ds_read_b128 v[80:83], v84 offset:4096
	s_waitcnt lgkmcnt(0)
	v_mfma_f32_32x32x16_bf16 v[96:111], v[80:83], v[120:123], v[96:111]
	ds_read_b128 v[80:83], v85 offset:6144
	ds_read_b128 v[196:199], v85 offset:6656
	s_waitcnt lgkmcnt(0)
	v_mfma_f32_32x32x16_bf16 v[96:111], v[80:83], v[124:127], v[96:111]
	v_mfma_f32_32x32x16_bf16 v[80:95], v[184:187], v[112:115], v[0:15]
	ds_read_b128 v[184:187], v200 offset:16384
	s_nop 9
	v_exp_f32_e32 v96, v96
	v_exp_f32_e32 v97, v97
	v_exp_f32_e32 v98, v98
	v_exp_f32_e32 v99, v99
	v_exp_f32_e32 v100, v100
	v_exp_f32_e32 v101, v101
	v_mfma_f32_32x32x16_bf16 v[80:95], v[188:191], v[116:119], v[80:95]
	v_exp_f32_e32 v102, v102
	v_exp_f32_e32 v103, v103
	v_cvt_pk_bf16_f32 v188, v96, v97
	v_cvt_pk_bf16_f32 v189, v98, v99
	v_cvt_pk_bf16_f32 v190, v100, v101
	v_cvt_pk_bf16_f32 v191, v102, v103
	v_exp_f32_e32 v104, v104
	v_mfma_f32_32x32x16_bf16 v[80:95], v[192:195], v[120:123], v[80:95]
	ds_read_b128 v[192:195], v200 offset:17408
	v_exp_f32_e32 v105, v105
	v_exp_f32_e32 v106, v106
	v_exp_f32_e32 v107, v107
	v_exp_f32_e32 v108, v108
	v_exp_f32_e32 v109, v109
	v_exp_f32_e32 v110, v110
	v_mfma_f32_32x32x16_bf16 v[80:95], v[196:199], v[124:127], v[80:95]
	v_exp_f32_e32 v111, v111
	s_waitcnt lgkmcnt(0)
	v_mfma_f32_32x32x16_bf16 v[64:79], v[184:187], v[188:191], v[64:79]
	ds_read_b128 v[184:187], v201 offset:16896
	ds_read_b128 v[196:199], v201 offset:17920
	s_nop 6
	v_exp_f32_e32 v80, v80
	v_exp_f32_e32 v81, v81
	v_exp_f32_e32 v82, v82
	v_exp_f32_e32 v83, v83
	v_exp_f32_e32 v84, v84
	v_exp_f32_e32 v85, v85
	s_waitcnt lgkmcnt(0)
	v_mfma_f32_32x32x16_bf16 v[48:63], v[184:187], v[188:191], v[48:63]
	ds_read_b128 v[184:187], v200 offset:20480
	v_exp_f32_e32 v86, v86
	v_exp_f32_e32 v87, v87
	v_exp_f32_e32 v88, v88
	v_exp_f32_e32 v89, v89
	v_exp_f32_e32 v90, v90
	v_exp_f32_e32 v91, v91
	v_mfma_f32_32x32x16_bf16 v[32:47], v[192:195], v[188:191], v[32:47]
	ds_read_b128 v[192:195], v200 offset:21504
	v_exp_f32_e32 v92, v92
	v_exp_f32_e32 v93, v93
	v_exp_f32_e32 v94, v94
	v_exp_f32_e32 v95, v95
	v_mfma_f32_32x32x16_bf16 v[16:31], v[196:199], v[188:191], v[16:31]
	v_cvt_pk_bf16_f32 v188, v104, v105
	v_cvt_pk_bf16_f32 v189, v106, v107
	v_cvt_pk_bf16_f32 v190, v108, v109
	v_cvt_pk_bf16_f32 v191, v110, v111
	s_waitcnt lgkmcnt(0)
	s_nop 0
	v_mfma_f32_32x32x16_bf16 v[64:79], v[184:187], v[188:191], v[64:79]
	ds_read_b128 v[184:187], v201 offset:20992
	ds_read_b128 v[196:199], v201 offset:22016
	s_waitcnt lgkmcnt(0)
	v_mfma_f32_32x32x16_bf16 v[48:63], v[184:187], v[188:191], v[48:63]
	ds_read_b128 v[184:187], v200 offset:24576
	v_mfma_f32_32x32x16_bf16 v[32:47], v[192:195], v[188:191], v[32:47]
	ds_read_b128 v[192:195], v200 offset:25600
	v_mfma_f32_32x32x16_bf16 v[16:31], v[196:199], v[188:191], v[16:31]
	v_cvt_pk_bf16_f32 v188, v80, v81
	v_cvt_pk_bf16_f32 v189, v82, v83
	v_cvt_pk_bf16_f32 v190, v84, v85
	v_cvt_pk_bf16_f32 v191, v86, v87
	s_waitcnt lgkmcnt(0)
	s_nop 0
	v_mfma_f32_32x32x16_bf16 v[64:79], v[184:187], v[188:191], v[64:79]
	ds_read_b128 v[184:187], v201 offset:25088
	ds_read_b128 v[196:199], v201 offset:26112
	s_waitcnt lgkmcnt(0)
	v_mfma_f32_32x32x16_bf16 v[48:63], v[184:187], v[188:191], v[48:63]
	ds_read_b128 v[184:187], v200 offset:28672
	v_mfma_f32_32x32x16_bf16 v[32:47], v[192:195], v[188:191], v[32:47]
	ds_read_b128 v[192:195], v200 offset:29696
	v_mfma_f32_32x32x16_bf16 v[16:31], v[196:199], v[188:191], v[16:31]
	v_cvt_pk_bf16_f32 v188, v88, v89
	v_cvt_pk_bf16_f32 v189, v90, v91
	v_cvt_pk_bf16_f32 v190, v92, v93
	v_cvt_pk_bf16_f32 v191, v94, v95
	s_waitcnt lgkmcnt(0)
	s_nop 0
	v_mfma_f32_32x32x16_bf16 v[64:79], v[184:187], v[188:191], v[64:79]
	ds_read_b128 v[184:187], v201 offset:29184
	ds_read_b128 v[196:199], v201 offset:30208
	s_waitcnt lgkmcnt(0)
	v_mfma_f32_32x32x16_bf16 v[48:63], v[184:187], v[188:191], v[48:63]
	s_cbranch_vccnz .Lcjd_skip_0
	s_and_b32 s99, s49, 0x18000
	v_add_u32_e32 v208, s99, v182
	v_add_u32_e32 v223, 0x4000, v208
	v_readfirstlane_b32 s99, v208
	s_mov_b32 m0, s99
	v_readfirstlane_b32 s99, v223
	v_add_u32_e32 v208, 0x6000, v208
	global_load_lds_dwordx4 v[164:165], off
	s_mov_b32 m0, s99
	v_readfirstlane_b32 s99, v208
	global_load_lds_dwordx4 v[166:167], off
	v_lshl_add_u64 v[166:167], v[166:167], 0, s[10:11]
	s_mov_b32 m0, s99
	s_nop 0
	global_load_lds_dwordx4 v[166:167], off

.Lcjh_done_0:
	v_mfma_f32_32x32x16_bf16 v[32:47], v[192:195], v[188:191], v[32:47]
	v_mfma_f32_32x32x16_bf16 v[16:31], v[196:199], v[188:191], v[16:31]
	s_cbranch_vccz .Lcj_cnt_0
	s_waitcnt vmcnt(0)
	s_branch .LBB0_1448

.LBB0_1459:
	s_add_i32 s18, s22, 0xfffe8000
	s_and_b32 s18, s18, 0x18000
	s_add_i32 s18, s18, 0
	v_add3_u32 v84, s18, v177, v176
	ds_read_b128 v[80:83], v84
	ds_read_b128 v[152:155], v84 offset:512
	v_add3_u32 v85, s18, v178, v176
	v_add3_u32 v84, s18, v179, v176
	v_add_u32_e32 v209, s18, v168
	v_add_u32_e32 v211, s18, v169
	s_and_b64 vcc, exec, s[16:17]
	s_waitcnt lgkmcnt(0)
	v_mfma_f32_32x32x16_bf16 v[96:111], v[80:83], v[112:115], v[0:15]
	ds_read_b128 v[80:83], v85 offset:2048
	ds_read_b128 v[156:159], v85 offset:2560
	v_add3_u32 v85, s18, v180, v176
	s_mov_b64 s[18:19], -1
	ds_read_b128 v[160:163], v84 offset:4608
	s_waitcnt lgkmcnt(0)
	v_mfma_f32_32x32x16_bf16 v[96:111], v[80:83], v[116:119], v[96:111]
	ds_read_b128 v[80:83], v84 offset:4096
	s_waitcnt lgkmcnt(0)
	v_mfma_f32_32x32x16_bf16 v[96:111], v[80:83], v[120:123], v[96:111]
	ds_read_b128 v[80:83], v85 offset:6144
	ds_read_b128 v[218:221], v85 offset:6656
	s_waitcnt lgkmcnt(0)
	v_mfma_f32_32x32x16_bf16 v[96:111], v[80:83], v[124:127], v[96:111]
	v_mfma_f32_32x32x16_bf16 v[80:95], v[152:155], v[112:115], v[0:15]
	ds_read_b128 v[152:155], v209 offset:16384
	s_nop 9
	v_exp_f32_e32 v96, v96
	v_exp_f32_e32 v97, v97
	v_exp_f32_e32 v98, v98
	v_exp_f32_e32 v99, v99
	v_exp_f32_e32 v100, v100
	v_exp_f32_e32 v101, v101
	v_mfma_f32_32x32x16_bf16 v[80:95], v[156:159], v[116:119], v[80:95]
	v_exp_f32_e32 v102, v102
	v_exp_f32_e32 v103, v103
	v_cvt_pk_bf16_f32 v156, v96, v97
	v_cvt_pk_bf16_f32 v157, v98, v99
	v_cvt_pk_bf16_f32 v158, v100, v101
	v_cvt_pk_bf16_f32 v159, v102, v103
	v_exp_f32_e32 v104, v104
	v_mfma_f32_32x32x16_bf16 v[80:95], v[160:163], v[120:123], v[80:95]
	ds_read_b128 v[160:163], v209 offset:17408
	v_exp_f32_e32 v105, v105
	v_exp_f32_e32 v106, v106
	v_exp_f32_e32 v107, v107
	v_exp_f32_e32 v108, v108
	v_exp_f32_e32 v109, v109
	v_exp_f32_e32 v110, v110
	v_mfma_f32_32x32x16_bf16 v[80:95], v[218:221], v[124:127], v[80:95]
	v_exp_f32_e32 v111, v111
	s_waitcnt lgkmcnt(0)
	v_mfma_f32_32x32x16_bf16 v[64:79], v[152:155], v[156:159], v[64:79]
	ds_read_b128 v[152:155], v211 offset:16896
	ds_read_b128 v[218:221], v211 offset:17920
	s_nop 6
	v_exp_f32_e32 v80, v80
	v_exp_f32_e32 v81, v81
	v_exp_f32_e32 v82, v82
	v_exp_f32_e32 v83, v83
	v_exp_f32_e32 v84, v84
	v_exp_f32_e32 v85, v85
	s_waitcnt lgkmcnt(0)
	v_mfma_f32_32x32x16_bf16 v[48:63], v[152:155], v[156:159], v[48:63]
	ds_read_b128 v[152:155], v209 offset:20480
	v_exp_f32_e32 v86, v86
	v_exp_f32_e32 v87, v87
	v_exp_f32_e32 v88, v88
	v_exp_f32_e32 v89, v89
	v_exp_f32_e32 v90, v90
	v_exp_f32_e32 v91, v91
	v_mfma_f32_32x32x16_bf16 v[32:47], v[160:163], v[156:159], v[32:47]
	ds_read_b128 v[160:163], v209 offset:21504
	v_exp_f32_e32 v92, v92
	v_exp_f32_e32 v93, v93
	v_exp_f32_e32 v94, v94
	v_exp_f32_e32 v95, v95
	v_mfma_f32_32x32x16_bf16 v[16:31], v[218:221], v[156:159], v[16:31]
	v_cvt_pk_bf16_f32 v156, v104, v105
	v_cvt_pk_bf16_f32 v157, v106, v107
	v_cvt_pk_bf16_f32 v158, v108, v109
	v_cvt_pk_bf16_f32 v159, v110, v111
	s_waitcnt lgkmcnt(0)
	s_nop 0
	v_mfma_f32_32x32x16_bf16 v[64:79], v[152:155], v[156:159], v[64:79]
	ds_read_b128 v[152:155], v211 offset:20992
	ds_read_b128 v[218:221], v211 offset:22016
	s_waitcnt lgkmcnt(0)
	v_mfma_f32_32x32x16_bf16 v[48:63], v[152:155], v[156:159], v[48:63]
	ds_read_b128 v[152:155], v209 offset:24576
	v_mfma_f32_32x32x16_bf16 v[32:47], v[160:163], v[156:159], v[32:47]
	ds_read_b128 v[160:163], v209 offset:25600
	v_mfma_f32_32x32x16_bf16 v[16:31], v[218:221], v[156:159], v[16:31]
	v_cvt_pk_bf16_f32 v156, v80, v81
	v_cvt_pk_bf16_f32 v157, v82, v83
	v_cvt_pk_bf16_f32 v158, v84, v85
	v_cvt_pk_bf16_f32 v159, v86, v87
	s_waitcnt lgkmcnt(0)
	s_nop 0
	v_mfma_f32_32x32x16_bf16 v[64:79], v[152:155], v[156:159], v[64:79]
	ds_read_b128 v[152:155], v211 offset:25088
	ds_read_b128 v[218:221], v211 offset:26112
	s_waitcnt lgkmcnt(0)
	v_mfma_f32_32x32x16_bf16 v[48:63], v[152:155], v[156:159], v[48:63]
	ds_read_b128 v[152:155], v209 offset:28672
	v_mfma_f32_32x32x16_bf16 v[32:47], v[160:163], v[156:159], v[32:47]
	ds_read_b128 v[160:163], v209 offset:29696
	v_mfma_f32_32x32x16_bf16 v[16:31], v[218:221], v[156:159], v[16:31]
	v_cvt_pk_bf16_f32 v156, v88, v89
	v_cvt_pk_bf16_f32 v157, v90, v91
	v_cvt_pk_bf16_f32 v158, v92, v93
	v_cvt_pk_bf16_f32 v159, v94, v95
	s_waitcnt lgkmcnt(0)
	s_nop 0
	v_mfma_f32_32x32x16_bf16 v[64:79], v[152:155], v[156:159], v[64:79]
	ds_read_b128 v[152:155], v211 offset:29184
	ds_read_b128 v[218:221], v211 offset:30208
	s_waitcnt lgkmcnt(0)
	v_mfma_f32_32x32x16_bf16 v[48:63], v[152:155], v[156:159], v[48:63]
	s_cbranch_vccnz .Lcjd_skip_1
	s_and_b32 s99, s22, 0x18000
	v_add_u32_e32 v208, s99, v182
	v_add_u32_e32 v223, 0x4000, v208
	v_readfirstlane_b32 s99, v208
	s_mov_b32 m0, s99
	v_readfirstlane_b32 s99, v223
	v_add_u32_e32 v208, 0x6000, v208
	global_load_lds_dwordx4 v[150:151], off
	s_mov_b32 m0, s99
	v_readfirstlane_b32 s99, v208
	global_load_lds_dwordx4 v[148:149], off
	v_lshl_add_u64 v[148:149], v[148:149], 0, s[10:11]
	s_mov_b32 m0, s99
	s_nop 0
	global_load_lds_dwordx4 v[148:149], off

.Lcjh_done_1:
	v_mfma_f32_32x32x16_bf16 v[32:47], v[160:163], v[156:159], v[32:47]
	v_mfma_f32_32x32x16_bf16 v[16:31], v[218:221], v[156:159], v[16:31]
	s_cbranch_vccz .Lcj_cnt_1
	s_waitcnt vmcnt(0)
	s_branch .LBB0_1456
